# MLA latent attention step restructured: QK of tile 1 interleaved with softmax of tile 0 (second score buffer, 6-deep K fragment ring)
# speedup vs baseline: 1.0389x; 1.0074x over previous
.LBB0_786:
	s_bitcmp1_b32 s2, 0
	s_cselect_b32 s2, 0xa000, 0
	v_add_u32_e32 v96, s2, v95
	ds_read_b128 v[172:175], v96
	ds_read_b128 v[176:179], v96 offset:1024
	ds_read_b128 v[188:191], v96 offset:2048
	ds_read_b128 v[192:195], v96 offset:3072
	ds_read_b128 v[198:201], v96 offset:4096
	ds_read_b128 v[202:205], v96 offset:5120
	s_waitcnt lgkmcnt(5)
	v_mfma_f32_32x32x16_bf16 v[64:79], v[172:175], v[82:85], 0
	ds_read_b128 v[172:175], v96 offset:6144
	s_waitcnt lgkmcnt(5)
	v_mfma_f32_32x32x16_bf16 v[64:79], v[176:179], v[86:89], v[64:79]
	ds_read_b128 v[176:179], v96 offset:7168
	s_waitcnt lgkmcnt(5)
	v_mfma_f32_32x32x16_bf16 v[64:79], v[188:191], v[90:93], v[64:79]
	ds_read_b128 v[188:191], v96 offset:8192
	s_waitcnt lgkmcnt(5)
	v_mfma_f32_32x32x16_bf16 v[64:79], v[192:195], v[112:115], v[64:79]
	ds_read_b128 v[192:195], v96 offset:9216
	s_waitcnt lgkmcnt(5)
	v_mfma_f32_32x32x16_bf16 v[64:79], v[198:201], v[116:119], v[64:79]
	ds_read_b128 v[198:201], v96 offset:10240
	s_waitcnt lgkmcnt(5)
	v_mfma_f32_32x32x16_bf16 v[64:79], v[202:205], v[120:123], v[64:79]
	ds_read_b128 v[202:205], v96 offset:11264
	s_waitcnt lgkmcnt(5)
	v_mfma_f32_32x32x16_bf16 v[64:79], v[172:175], v[124:127], v[64:79]
	ds_read_b128 v[172:175], v96 offset:20480
	s_waitcnt lgkmcnt(5)
	v_mfma_f32_32x32x16_bf16 v[64:79], v[176:179], v[128:131], v[64:79]
	ds_read_b128 v[176:179], v96 offset:21504
	s_waitcnt lgkmcnt(5)
	v_mfma_f32_32x32x16_bf16 v[64:79], v[188:191], v[132:135], v[64:79]
	ds_read_b128 v[188:191], v96 offset:22528
	s_waitcnt lgkmcnt(5)
	v_mfma_f32_32x32x16_bf16 v[64:79], v[192:195], v[136:139], v[64:79]
	ds_read_b128 v[192:195], v96 offset:23552
	s_waitcnt lgkmcnt(5)
	v_mfma_f32_32x32x16_bf16 v[64:79], v[198:201], v[140:143], v[64:79]
	ds_read_b128 v[198:201], v96 offset:24576
	s_waitcnt lgkmcnt(5)
	v_mfma_f32_32x32x16_bf16 v[64:79], v[202:205], v[144:147], v[64:79]
	ds_read_b128 v[202:205], v96 offset:25600
	ds_read_b128 v[148:151], v96 offset:12288
	ds_read_b128 v[106:109], v96 offset:13312
	ds_read_b128 v[98:101], v96 offset:14336
	ds_read_b128 v[102:105], v96 offset:15360
	s_waitcnt lgkmcnt(9)
	v_mfma_f32_32x32x16_bf16 v[218:233], v[172:175], v[82:85], 0
	ds_read_b128 v[172:175], v96 offset:26624
	s_waitcnt lgkmcnt(9)
	v_mfma_f32_32x32x16_bf16 v[218:233], v[176:179], v[86:89], v[218:233]
	ds_read_b128 v[176:179], v96 offset:27648
	s_nop 3
	v_max_f32_e32 v110, v65, v65
	v_max_f32_e32 v111, v64, v64
	v_max_f32_e32 v110, v111, v110
	v_max3_f32 v110, v110, v66, v67
	v_max3_f32 v110, v110, v68, v69
	v_max3_f32 v110, v110, v70, v71
	v_max3_f32 v110, v110, v72, v73
	v_max3_f32 v110, v110, v74, v75
	v_max3_f32 v110, v110, v76, v77
	v_max3_f32 v110, v110, v78, v79
	v_mov_b32_e32 v111, v110
	s_nop 1
	v_permlane32_swap_b32_e32 v110, v111
	v_max_f32_e32 v111, v111, v111
	v_max_f32_e32 v110, v110, v110
	v_max_f32_e32 v110, v110, v111
	v_mul_f32_e32 v111, 0x3dd53b94, v110
	v_add_f32_e32 v110, 0x41000000, v80
	v_cmp_le_f32_e32 vcc, v111, v110
	s_cmp_eq_u64 vcc, exec
	s_cbranch_scc1 .LBB0_788
	v_max_f32_e32 v110, v111, v111
	v_max_f32_e32 v111, v80, v80
	v_max_f32_e32 v111, v111, v110
	v_sub_f32_e32 v80, v80, v111
	v_exp_f32_e32 v80, v80
	v_add_f32_e32 v110, 0x41000000, v111
	v_mul_f32_e32 v81, v81, v80
	v_pk_mul_f32 v[62:63], v[62:63], v[80:81] op_sel_hi:[1,0]
	v_pk_mul_f32 v[60:61], v[60:61], v[80:81] op_sel_hi:[1,0]
	v_pk_mul_f32 v[58:59], v[58:59], v[80:81] op_sel_hi:[1,0]
	v_pk_mul_f32 v[56:57], v[56:57], v[80:81] op_sel_hi:[1,0]
	v_pk_mul_f32 v[54:55], v[54:55], v[80:81] op_sel_hi:[1,0]
	v_pk_mul_f32 v[52:53], v[52:53], v[80:81] op_sel_hi:[1,0]
	v_pk_mul_f32 v[50:51], v[50:51], v[80:81] op_sel_hi:[1,0]
	v_pk_mul_f32 v[48:49], v[48:49], v[80:81] op_sel_hi:[1,0]
	v_pk_mul_f32 v[46:47], v[46:47], v[80:81] op_sel_hi:[1,0]
	v_pk_mul_f32 v[44:45], v[44:45], v[80:81] op_sel_hi:[1,0]
	v_pk_mul_f32 v[42:43], v[42:43], v[80:81] op_sel_hi:[1,0]
	v_pk_mul_f32 v[40:41], v[40:41], v[80:81] op_sel_hi:[1,0]
	v_pk_mul_f32 v[38:39], v[38:39], v[80:81] op_sel_hi:[1,0]
	v_pk_mul_f32 v[36:37], v[36:37], v[80:81] op_sel_hi:[1,0]
	v_pk_mul_f32 v[34:35], v[34:35], v[80:81] op_sel_hi:[1,0]
	v_pk_mul_f32 v[32:33], v[32:33], v[80:81] op_sel_hi:[1,0]
	v_pk_mul_f32 v[30:31], v[30:31], v[80:81] op_sel_hi:[1,0]
	v_pk_mul_f32 v[28:29], v[28:29], v[80:81] op_sel_hi:[1,0]
	v_pk_mul_f32 v[26:27], v[26:27], v[80:81] op_sel_hi:[1,0]
	v_pk_mul_f32 v[24:25], v[24:25], v[80:81] op_sel_hi:[1,0]
	v_pk_mul_f32 v[22:23], v[22:23], v[80:81] op_sel_hi:[1,0]
	v_pk_mul_f32 v[20:21], v[20:21], v[80:81] op_sel_hi:[1,0]
	v_pk_mul_f32 v[18:19], v[18:19], v[80:81] op_sel_hi:[1,0]
	v_pk_mul_f32 v[16:17], v[16:17], v[80:81] op_sel_hi:[1,0]
	v_pk_mul_f32 v[14:15], v[14:15], v[80:81] op_sel_hi:[1,0]
	v_pk_mul_f32 v[12:13], v[12:13], v[80:81] op_sel_hi:[1,0]
	v_pk_mul_f32 v[10:11], v[10:11], v[80:81] op_sel_hi:[1,0]
	v_pk_mul_f32 v[8:9], v[8:9], v[80:81] op_sel_hi:[1,0]
	v_pk_mul_f32 v[6:7], v[6:7], v[80:81] op_sel_hi:[1,0]
	v_pk_mul_f32 v[4:5], v[4:5], v[80:81] op_sel_hi:[1,0]
	v_pk_mul_f32 v[2:3], v[2:3], v[80:81] op_sel_hi:[1,0]
	v_pk_mul_f32 v[0:1], v[0:1], v[80:81] op_sel_hi:[1,0]
	v_mov_b32_e32 v80, v111
.LBB0_788:
	s_waitcnt lgkmcnt(9)
	v_mfma_f32_32x32x16_bf16 v[218:233], v[188:191], v[90:93], v[218:233]
	ds_read_b128 v[188:191], v96 offset:28672
	v_fma_f32 v64, v64, s80, -v80
	v_exp_f32_e32 v64, v64
	v_fma_f32 v65, v65, s80, -v80
	v_exp_f32_e32 v65, v65
	v_fma_f32 v66, v66, s80, -v80
	v_exp_f32_e32 v66, v66
	s_waitcnt lgkmcnt(9)
	v_mfma_f32_32x32x16_bf16 v[218:233], v[192:195], v[112:115], v[218:233]
	ds_read_b128 v[192:195], v96 offset:29696
	v_fma_f32 v67, v67, s80, -v80
	v_exp_f32_e32 v67, v67
	v_fma_f32 v68, v68, s80, -v80
	v_add_f32_e32 v111, 0, v64
	v_exp_f32_e32 v68, v68
	v_fma_f32 v69, v69, s80, -v80
	s_waitcnt lgkmcnt(9)
	v_mfma_f32_32x32x16_bf16 v[218:233], v[198:201], v[116:119], v[218:233]
	ds_read_b128 v[198:201], v96 offset:30720
	v_add_f32_e32 v111, v65, v111
	v_exp_f32_e32 v69, v69
	v_fma_f32 v70, v70, s80, -v80
	v_add_f32_e32 v111, v66, v111
	v_exp_f32_e32 v70, v70
	v_fma_f32 v71, v71, s80, -v80
	s_waitcnt lgkmcnt(9)
	v_mfma_f32_32x32x16_bf16 v[218:233], v[202:205], v[120:123], v[218:233]
	ds_read_b128 v[202:205], v96 offset:31744
	v_add_f32_e32 v111, v67, v111
	v_exp_f32_e32 v71, v71
	v_fma_f32 v72, v72, s80, -v80
	v_add_f32_e32 v111, v68, v111
	v_exp_f32_e32 v159, v72
	v_add_f32_e32 v111, v69, v111
	s_waitcnt lgkmcnt(5)
	v_mfma_f32_32x32x16_bf16 v[218:233], v[172:175], v[124:127], v[218:233]
	v_add_f32_e32 v111, v70, v111
	v_add_f32_e32 v111, v71, v111
	v_fma_f32 v73, v73, s80, -v80
	v_add_f32_e32 v72, v159, v111
	v_exp_f32_e32 v111, v73
	v_fma_f32 v73, v74, s80, -v80
	s_waitcnt lgkmcnt(4)
	v_mfma_f32_32x32x16_bf16 v[218:233], v[176:179], v[128:131], v[218:233]
	v_exp_f32_e32 v165, v73
	v_fma_f32 v73, v75, s80, -v80
	v_exp_f32_e32 v166, v73
	v_fma_f32 v73, v76, s80, -v80
	v_exp_f32_e32 v167, v73
	v_fma_f32 v73, v77, s80, -v80
	s_waitcnt lgkmcnt(3)
	v_mfma_f32_32x32x16_bf16 v[218:233], v[188:191], v[132:135], v[218:233]
	v_add_f32_e32 v72, v111, v72
	v_exp_f32_e32 v168, v73
	v_fma_f32 v73, v78, s80, -v80
	v_add_f32_e32 v72, v165, v72
	v_exp_f32_e32 v169, v73
	v_fma_f32 v73, v79, s80, -v80
	s_waitcnt lgkmcnt(2)
	v_mfma_f32_32x32x16_bf16 v[218:233], v[192:195], v[136:139], v[218:233]
	v_add_f32_e32 v72, v166, v72
	v_exp_f32_e32 v170, v73
	v_add_f32_e32 v72, v167, v72
	v_cvt_pk_bf16_f32 v64, v64, v65
	v_cvt_pk_bf16_f32 v65, v66, v67
	v_cvt_pk_bf16_f32 v66, v68, v69
	s_waitcnt lgkmcnt(1)
	v_mfma_f32_32x32x16_bf16 v[218:233], v[198:201], v[140:143], v[218:233]
	v_cvt_pk_bf16_f32 v67, v70, v71
	v_add_f32_e32 v72, v168, v72
	v_add_f32_e32 v72, v169, v72
	v_add_f32_e32 v72, v170, v72
	v_mov_b32_e32 v73, v72
	s_nop 1
	s_waitcnt lgkmcnt(0)
	v_mfma_f32_32x32x16_bf16 v[218:233], v[202:205], v[144:147], v[218:233]
	v_permlane32_swap_b32_e32 v72, v73
	v_add_f32_e32 v72, v72, v73
	v_add_f32_e32 v81, v81, v72
	s_waitcnt lgkmcnt(9)
	v_mfma_f32_32x32x16_bf16 v[48:63], v[148:151], v[64:67], v[48:63]
	ds_read_b128 v[234:237], v96 offset:16384
	ds_read_b128 v[68:71], v96 offset:17408
	ds_read_b128 v[72:75], v96 offset:18432
	ds_read_b128 v[76:79], v96 offset:19456
	s_waitcnt lgkmcnt(12)
	v_mfma_f32_32x32x16_bf16 v[32:47], v[106:109], v[64:67], v[32:47]
	s_waitcnt lgkmcnt(11)
	v_mfma_f32_32x32x16_bf16 v[16:31], v[98:101], v[64:67], v[16:31]
	v_cvt_pk_bf16_f32 v98, v159, v111
	v_cvt_pk_bf16_f32 v99, v165, v166
	v_cvt_pk_bf16_f32 v100, v167, v168
	v_cvt_pk_bf16_f32 v101, v169, v170
	s_waitcnt lgkmcnt(10)
	v_mfma_f32_32x32x16_bf16 v[0:15], v[102:105], v[64:67], v[0:15]
	ds_read_b128 v[148:151], v96 offset:32768
	ds_read_b128 v[106:109], v96 offset:33792
	ds_read_b128 v[102:105], v96 offset:35840
	s_waitcnt lgkmcnt(6)
	v_mfma_f32_32x32x16_bf16 v[48:63], v[234:237], v[98:101], v[48:63]
	s_waitcnt lgkmcnt(5)
	v_mfma_f32_32x32x16_bf16 v[32:47], v[68:71], v[98:101], v[32:47]
	s_waitcnt lgkmcnt(4)
	v_mfma_f32_32x32x16_bf16 v[16:31], v[72:75], v[98:101], v[16:31]
	s_waitcnt lgkmcnt(3)
	v_mfma_f32_32x32x16_bf16 v[0:15], v[76:79], v[98:101], v[0:15]
	ds_read_b128 v[98:101], v96 offset:34816
	v_max_f32_e32 v111, v219, v219
	v_max_f32_e32 v159, v218, v218
	v_max_f32_e32 v111, v159, v111
	v_max3_f32 v111, v111, v220, v221
	v_max3_f32 v111, v111, v222, v223
	v_max3_f32 v111, v111, v224, v225
	v_max3_f32 v111, v111, v226, v227
	v_max3_f32 v111, v111, v228, v229
	v_max3_f32 v111, v111, v230, v231
	v_max3_f32 v111, v111, v232, v233
	v_mov_b32_e32 v159, v111
	s_nop 1
	v_permlane32_swap_b32_e32 v111, v159
	v_max_f32_e32 v159, v159, v159
	v_max_f32_e32 v111, v111, v111
	v_max_f32_e32 v111, v111, v159
	v_mul_f32_e32 v111, 0x3dd53b94, v111
	v_cmp_le_f32_e32 vcc, v111, v110
	s_cmp_eq_u64 vcc, exec
	s_cbranch_scc1 .LBB0_790
	v_max_f32_e32 v110, v111, v111
	v_max_f32_e32 v111, v80, v80
	v_max_f32_e32 v111, v111, v110
	v_sub_f32_e32 v80, v80, v111
	v_exp_f32_e32 v80, v80
	v_xor_b32_e32 v110, 0x80000000, v111
	v_mul_f32_e32 v81, v81, v80
	v_pk_mul_f32 v[62:63], v[62:63], v[80:81] op_sel_hi:[1,0]
	v_pk_mul_f32 v[60:61], v[60:61], v[80:81] op_sel_hi:[1,0]
	v_pk_mul_f32 v[58:59], v[58:59], v[80:81] op_sel_hi:[1,0]
	v_pk_mul_f32 v[56:57], v[56:57], v[80:81] op_sel_hi:[1,0]
	v_pk_mul_f32 v[54:55], v[54:55], v[80:81] op_sel_hi:[1,0]
	v_pk_mul_f32 v[52:53], v[52:53], v[80:81] op_sel_hi:[1,0]
	v_pk_mul_f32 v[50:51], v[50:51], v[80:81] op_sel_hi:[1,0]
	v_pk_mul_f32 v[48:49], v[48:49], v[80:81] op_sel_hi:[1,0]
	v_pk_mul_f32 v[46:47], v[46:47], v[80:81] op_sel_hi:[1,0]
	v_pk_mul_f32 v[44:45], v[44:45], v[80:81] op_sel_hi:[1,0]
	v_pk_mul_f32 v[42:43], v[42:43], v[80:81] op_sel_hi:[1,0]
	v_pk_mul_f32 v[40:41], v[40:41], v[80:81] op_sel_hi:[1,0]
	v_pk_mul_f32 v[38:39], v[38:39], v[80:81] op_sel_hi:[1,0]
	v_pk_mul_f32 v[36:37], v[36:37], v[80:81] op_sel_hi:[1,0]
	v_pk_mul_f32 v[34:35], v[34:35], v[80:81] op_sel_hi:[1,0]
	v_pk_mul_f32 v[32:33], v[32:33], v[80:81] op_sel_hi:[1,0]
	v_pk_mul_f32 v[30:31], v[30:31], v[80:81] op_sel_hi:[1,0]
	v_pk_mul_f32 v[28:29], v[28:29], v[80:81] op_sel_hi:[1,0]
	v_pk_mul_f32 v[26:27], v[26:27], v[80:81] op_sel_hi:[1,0]
	v_pk_mul_f32 v[24:25], v[24:25], v[80:81] op_sel_hi:[1,0]
	v_pk_mul_f32 v[22:23], v[22:23], v[80:81] op_sel_hi:[1,0]
	v_pk_mul_f32 v[20:21], v[20:21], v[80:81] op_sel_hi:[1,0]
	v_pk_mul_f32 v[18:19], v[18:19], v[80:81] op_sel_hi:[1,0]
	v_pk_mul_f32 v[16:17], v[16:17], v[80:81] op_sel_hi:[1,0]
	v_pk_mul_f32 v[14:15], v[14:15], v[80:81] op_sel_hi:[1,0]
	v_pk_mul_f32 v[12:13], v[12:13], v[80:81] op_sel_hi:[1,0]
	v_pk_mul_f32 v[10:11], v[10:11], v[80:81] op_sel_hi:[1,0]
	v_pk_mul_f32 v[8:9], v[8:9], v[80:81] op_sel_hi:[1,0]
	v_pk_mul_f32 v[6:7], v[6:7], v[80:81] op_sel_hi:[1,0]
	v_pk_mul_f32 v[4:5], v[4:5], v[80:81] op_sel_hi:[1,0]
	v_pk_mul_f32 v[2:3], v[2:3], v[80:81] op_sel_hi:[1,0]
	v_pk_mul_f32 v[0:1], v[0:1], v[80:81] op_sel_hi:[1,0]
	v_mov_b32_e32 v80, v111
	s_branch .LBB0_791

.LBB0_791:
	v_fmamk_f32 v218, v218, 0x3dd53b94, v110
	v_exp_f32_e32 v218, v218
	v_fmamk_f32 v219, v219, 0x3dd53b94, v110
	v_exp_f32_e32 v219, v219
	v_fmamk_f32 v220, v220, 0x3dd53b94, v110
	v_exp_f32_e32 v220, v220
	v_fmamk_f32 v221, v221, 0x3dd53b94, v110
	v_exp_f32_e32 v221, v221
	v_fmamk_f32 v222, v222, 0x3dd53b94, v110
	v_add_f32_e32 v111, 0, v218
	v_exp_f32_e32 v222, v222
	v_fmamk_f32 v223, v223, 0x3dd53b94, v110
	v_add_f32_e32 v111, v219, v111
	v_exp_f32_e32 v223, v223
	v_fmamk_f32 v224, v224, 0x3dd53b94, v110
	v_add_f32_e32 v111, v220, v111
	v_exp_f32_e32 v224, v224
	v_fmamk_f32 v225, v225, 0x3dd53b94, v110
	v_add_f32_e32 v111, v221, v111
	v_exp_f32_e32 v225, v225
	v_fmamk_f32 v226, v226, 0x3dd53b94, v110
	v_add_f32_e32 v111, v222, v111
	v_exp_f32_e32 v159, v226
	v_add_f32_e32 v111, v223, v111
	v_add_f32_e32 v111, v224, v111
	v_add_f32_e32 v111, v225, v111
	v_fmamk_f32 v227, v227, 0x3dd53b94, v110
	v_add_f32_e32 v226, v159, v111
	v_exp_f32_e32 v111, v227
	v_fmamk_f32 v227, v228, 0x3dd53b94, v110
	v_exp_f32_e32 v165, v227
	v_fmamk_f32 v227, v229, 0x3dd53b94, v110
	v_exp_f32_e32 v166, v227
	v_fmamk_f32 v227, v230, 0x3dd53b94, v110
	v_exp_f32_e32 v167, v227
	v_fmamk_f32 v227, v231, 0x3dd53b94, v110
	v_add_f32_e32 v226, v111, v226
	v_exp_f32_e32 v168, v227
	v_fmamk_f32 v227, v232, 0x3dd53b94, v110
	v_add_f32_e32 v226, v165, v226
	v_exp_f32_e32 v169, v227
	v_fmac_f32_e32 v110, 0x3dd53b94, v233
	v_add_f32_e32 v226, v166, v226
	v_exp_f32_e32 v110, v110
	v_add_f32_e32 v226, v167, v226
	v_add_f32_e32 v226, v168, v226
	v_add_f32_e32 v226, v169, v226
	v_add_f32_e32 v226, v110, v226
	v_cvt_pk_bf16_f32 v218, v218, v219
	v_cvt_pk_bf16_f32 v219, v220, v221
	v_cvt_pk_bf16_f32 v220, v222, v223
	v_cvt_pk_bf16_f32 v221, v224, v225
	v_mov_b32_e32 v227, v226
	s_nop 1
	v_permlane32_swap_b32_e32 v226, v227
	s_waitcnt lgkmcnt(3)
	v_mfma_f32_32x32x16_bf16 v[48:63], v[148:151], v[218:221], v[48:63]
	v_add_f32_e32 v226, v226, v227
	v_add_f32_e32 v81, v81, v226
	ds_read_b128 v[234:237], v96 offset:36864
	ds_read_b128 v[222:225], v96 offset:37888
	ds_read_b128 v[226:229], v96 offset:38912
	ds_read_b128 v[230:233], v96 offset:39936
	v_lshl_add_u64 v[160:161], v[160:161], 0, s[26:27]
	v_lshl_add_u64 v[162:163], v[162:163], 0, s[28:29]
	s_cmp_eq_u32 s5, 34
	s_waitcnt lgkmcnt(6)
	v_mfma_f32_32x32x16_bf16 v[32:47], v[106:109], v[218:221], v[32:47]
	s_waitcnt lgkmcnt(4)
	v_mfma_f32_32x32x16_bf16 v[16:31], v[98:101], v[218:221], v[16:31]
	v_cvt_pk_bf16_f32 v98, v159, v111
	v_cvt_pk_bf16_f32 v99, v165, v166
	v_cvt_pk_bf16_f32 v100, v167, v168
	v_cvt_pk_bf16_f32 v101, v169, v110
	s_waitcnt lgkmcnt(5)
	v_mfma_f32_32x32x16_bf16 v[0:15], v[102:105], v[218:221], v[0:15]
	s_waitcnt lgkmcnt(3)
	v_mfma_f32_32x32x16_bf16 v[48:63], v[234:237], v[98:101], v[48:63]
	s_waitcnt lgkmcnt(2)
	v_mfma_f32_32x32x16_bf16 v[32:47], v[222:225], v[98:101], v[32:47]
	s_waitcnt lgkmcnt(1)
	v_mfma_f32_32x32x16_bf16 v[16:31], v[226:229], v[98:101], v[16:31]
	s_waitcnt lgkmcnt(0)
	v_mfma_f32_32x32x16_bf16 v[0:15], v[230:233], v[98:101], v[0:15]
	s_cbranch_scc1 .LBB0_793
	s_mov_b32 s2, s5
	s_branch .LBB0_784
.LBB0_793:
	s_nop 0
	s_nop 0
	s_nop 0
	s_nop 0
	s_nop 0
	s_nop 0
	s_nop 0
	s_nop 0
	s_nop 0
	s_nop 0
	s_nop 0
	s_nop 0
	s_nop 0
	s_nop 0
	s_and_b32 s2, s4, 0x7f
	s_lshl_b32 s3, s2, 3
	v_readlane_b32 s5, v250, 0
	s_add_i32 s3, s3, s5
	v_mov_b32_e32 v64, 0x4400
	v_mad_u64_u32 v[134:135], s[6:7], s3, v64, v[154:155]
	s_cmpk_gt_u32 s4, 0x7f
	s_mov_b64 s[8:9], -1
	s_cbranch_scc0 .LBB0_801
	v_readlane_b32 s6, v250, 15
	v_readlane_b32 s7, v250, 16
	s_andn2_b64 vcc, exec, s[6:7]
	s_cbranch_vccnz .LBB0_800
	s_lshl_b32 s2, s2, 6
	v_readlane_b32 s3, v252, 21
	s_add_u32 s8, s3, s2
	v_readlane_b32 s2, v252, 22
	s_addc_u32 s9, s2, 0
	s_mov_b32 s2, 0x100001
	s_branch .LBB0_797
